# P0 scaled weight-transpose items (w_in, w_out): 8 scale + 8 row loads issued together instead of 8 serial round trips; split 12/20
# speedup vs baseline: 1.0034x; 1.0034x over previous
.LBB0_91:
	v_add_u32_e32 v32, s56, v2
	v_ashrrev_i32_e32 v33, 31, v32
	v_lshl_add_u64 v[30:31], s[54:55], 1, v[10:11]
	v_lshlrev_b64 v[34:35], 11, v[32:33]
	v_lshl_add_u64 v[34:35], v[30:31], 0, v[34:35]
	s_waitcnt lgkmcnt(0)
	ds_read2_b32 v[14:15], v27 offset1:33
	s_waitcnt lgkmcnt(0)
	v_cvt_pk_bf16_f32 v14, v14, v15
	ds_read2_b32 v[16:17], v27 offset0:66 offset1:99
	s_waitcnt lgkmcnt(0)
	v_cvt_pk_bf16_f32 v15, v16, v17
	ds_read2_b32 v[16:17], v27 offset0:132 offset1:165
	s_waitcnt lgkmcnt(0)
	v_cvt_pk_bf16_f32 v16, v16, v17
	ds_read2_b32 v[18:19], v27 offset0:198 offset1:231
	s_waitcnt lgkmcnt(0)
	v_cvt_pk_bf16_f32 v17, v18, v19
	global_store_dwordx4 v[34:35], v[14:17], off
	v_add_u32_e32 v34, 8, v32
	v_ashrrev_i32_e32 v35, 31, v34
	ds_read2_b32 v[18:19], v27 offset0:8 offset1:41
	s_waitcnt lgkmcnt(0)
	v_cvt_pk_bf16_f32 v14, v18, v19
	ds_read2_b32 v[16:17], v27 offset0:74 offset1:107
	v_lshlrev_b64 v[34:35], 11, v[34:35]
	s_waitcnt lgkmcnt(0)
	v_cvt_pk_bf16_f32 v15, v16, v17
	ds_read2_b32 v[16:17], v27 offset0:140 offset1:173
	v_lshl_add_u64 v[34:35], v[30:31], 0, v[34:35]
	s_waitcnt lgkmcnt(0)
	v_cvt_pk_bf16_f32 v16, v16, v17
	ds_read2_b32 v[18:19], v27 offset0:206 offset1:239
	s_waitcnt lgkmcnt(0)
	v_cvt_pk_bf16_f32 v17, v18, v19
	global_store_dwordx4 v[34:35], v[14:17], off
	v_add_u32_e32 v34, 16, v32
	ds_read2_b32 v[18:19], v27 offset0:16 offset1:49
	s_waitcnt lgkmcnt(0)
	v_cvt_pk_bf16_f32 v14, v18, v19
	ds_read2_b32 v[16:17], v27 offset0:82 offset1:115
	v_ashrrev_i32_e32 v35, 31, v34
	s_waitcnt lgkmcnt(0)
	v_cvt_pk_bf16_f32 v15, v16, v17
	ds_read2_b32 v[16:17], v27 offset0:148 offset1:181
	v_lshlrev_b64 v[34:35], 11, v[34:35]
	s_waitcnt lgkmcnt(0)
	v_cvt_pk_bf16_f32 v16, v16, v17
	ds_read2_b32 v[18:19], v27 offset0:214 offset1:247
	s_waitcnt lgkmcnt(0)
	v_cvt_pk_bf16_f32 v17, v18, v19
	v_lshl_add_u64 v[34:35], v[30:31], 0, v[34:35]
	ds_read2_b32 v[18:19], v27 offset0:24 offset1:57
	global_store_dwordx4 v[34:35], v[14:17], off
	v_add_u32_e32 v32, 24, v32
	v_ashrrev_i32_e32 v33, 31, v32
	s_waitcnt lgkmcnt(0)
	v_cvt_pk_bf16_f32 v14, v18, v19
	ds_read2_b32 v[16:17], v27 offset0:90 offset1:123
	s_waitcnt lgkmcnt(0)
	v_cvt_pk_bf16_f32 v15, v16, v17
	ds_read2_b32 v[16:17], v27 offset0:156 offset1:189
	s_waitcnt lgkmcnt(0)
	v_cvt_pk_bf16_f32 v16, v16, v17
	ds_read2_b32 v[18:19], v27 offset0:222 offset1:255
	v_lshlrev_b64 v[32:33], 11, v[32:33]
	s_waitcnt lgkmcnt(0)
	v_cvt_pk_bf16_f32 v17, v18, v19
	v_lshl_add_u64 v[18:19], v[30:31], 0, v[32:33]
	global_store_dwordx4 v[18:19], v[14:17], off
	s_waitcnt lgkmcnt(0)

.LBB0_93:
	s_cmpk_gt_i32 s64, 0x2ff
	s_mov_b64 s[4:5], -1
	s_cbranch_scc0 .LBB0_131
	s_cmpk_gt_u32 s64, 0x37f
	s_cbranch_scc0 .LBB0_128
	v_mov_b32_e32 v4, s72
	ds_read_b64 v[18:19], v4
	v_mov_b32_e32 v4, s73
	ds_read_b128 v[14:17], v4
	s_and_b32 s10, s68, 0x7fffffc0
	v_or_b32_e32 v4, s10, v2
	s_waitcnt lgkmcnt(1)
	v_readfirstlane_b32 s78, v18
	v_readfirstlane_b32 s79, v19
	s_waitcnt lgkmcnt(0)
	v_readfirstlane_b32 s4, v14
	v_readfirstlane_b32 s5, v15
	v_readfirstlane_b32 s54, v16
	v_readfirstlane_b32 s55, v17
	s_cmp_lg_u64 s[4:5], 0
	s_cselect_b64 s[58:59], -1, 0
	s_cmp_lg_u64 s[54:55], 0
	s_cselect_b64 s[56:57], -1, 0
	v_add_u32_e32 v16, s10, v2
	v_mov_b32_e32 v17, v5
	v_lshlrev_b64 v[18:19], 2, v[16:17]
	s_and_b64 vcc, exec, s[58:59]
	s_cbranch_vccz .Lwo_noscale
	s_cmpk_gt_u32 s10, 0x1ff
	s_cselect_b64 s[60:61], -1, 0
	s_and_b64 s[60:61], s[60:61], s[56:57]
	v_lshl_add_u64 v[30:31], s[4:5], 0, v[18:19]
	v_lshl_add_u64 v[32:33], s[54:55], 0, v[18:19]
	v_lshl_add_u64 v[34:35], v[30:31], 0, 0
	v_lshl_add_u64 v[18:19], v[32:33], 0, s[12:13]
	v_cndmask_b32_e64 v35, v35, v19, s[60:61]
	v_cndmask_b32_e64 v34, v34, v18, s[60:61]
	global_load_dword v92, v[34:35], off
	v_lshl_add_u64 v[34:35], v[30:31], 0, 32
	v_lshl_add_u64 v[18:19], v[32:33], 0, s[14:15]
	v_cndmask_b32_e64 v35, v35, v19, s[60:61]
	v_cndmask_b32_e64 v34, v34, v18, s[60:61]
	global_load_dword v94, v[34:35], off
	v_lshl_add_u64 v[34:35], v[30:31], 0, 64
	v_lshl_add_u64 v[18:19], v[32:33], 0, s[16:17]
	v_cndmask_b32_e64 v35, v35, v19, s[60:61]
	v_cndmask_b32_e64 v34, v34, v18, s[60:61]
	global_load_dword v96, v[34:35], off
	v_lshl_add_u64 v[34:35], v[30:31], 0, s[18:19]
	v_lshl_add_u64 v[18:19], v[32:33], 0, s[20:21]
	v_cndmask_b32_e64 v35, v35, v19, s[60:61]
	v_cndmask_b32_e64 v34, v34, v18, s[60:61]
	global_load_dword v98, v[34:35], off
	v_lshl_add_u64 v[34:35], v[30:31], 0, s[22:23]
	v_lshl_add_u64 v[18:19], v[32:33], 0, s[24:25]
	v_cndmask_b32_e64 v35, v35, v19, s[60:61]
	v_cndmask_b32_e64 v34, v34, v18, s[60:61]
	global_load_dword v100, v[34:35], off
	v_lshl_add_u64 v[34:35], v[30:31], 0, s[26:27]
	v_lshl_add_u64 v[18:19], v[32:33], 0, s[28:29]
	v_cndmask_b32_e64 v35, v35, v19, s[60:61]
	v_cndmask_b32_e64 v34, v34, v18, s[60:61]
	global_load_dword v102, v[34:35], off
	v_lshl_add_u64 v[34:35], v[30:31], 0, s[30:31]
	v_lshl_add_u64 v[18:19], v[32:33], 0, s[34:35]
	v_cndmask_b32_e64 v35, v35, v19, s[60:61]
	v_cndmask_b32_e64 v34, v34, v18, s[60:61]
	global_load_dword v104, v[34:35], off
	v_lshl_add_u64 v[34:35], v[30:31], 0, s[50:51]
	v_lshl_add_u64 v[18:19], v[32:33], 0, s[52:53]
	v_cndmask_b32_e64 v35, v35, v19, s[60:61]
	v_cndmask_b32_e64 v34, v34, v18, s[60:61]
	global_load_dword v106, v[34:35], off
	s_branch .Lwo_w
.Lwo_noscale:
	v_mov_b32_e32 v92, 1.0
	v_mov_b32_e32 v94, 1.0
	v_mov_b32_e32 v96, 1.0
	v_mov_b32_e32 v98, 1.0
	v_mov_b32_e32 v100, 1.0
	v_mov_b32_e32 v102, 1.0
	v_mov_b32_e32 v104, 1.0
	v_mov_b32_e32 v106, 1.0
.Lwo_w:
	s_and_b32 s77, s66, 0x3e0
	s_lshl_b32 s60, s77, 2
	s_add_u32 s60, s78, s60
	s_addc_u32 s61, s79, 0
	v_mov_b32_e32 v13, v5
	v_lshl_add_u64 v[14:15], s[60:61], 0, v[12:13]
	v_or_b32_e32 v4, s10, v2
	v_lshlrev_b64 v[16:17], 12, v[4:5]
	v_lshl_add_u64 v[16:17], v[14:15], 0, v[16:17]
	global_load_dwordx4 v[60:63], v[16:17], off nt
	v_or_b32_e32 v4, s10, v20
	v_lshlrev_b64 v[16:17], 12, v[4:5]
	v_lshl_add_u64 v[16:17], v[14:15], 0, v[16:17]
	global_load_dwordx4 v[64:67], v[16:17], off nt
	v_or_b32_e32 v4, s10, v21
	v_lshlrev_b64 v[16:17], 12, v[4:5]
	v_lshl_add_u64 v[16:17], v[14:15], 0, v[16:17]
	global_load_dwordx4 v[68:71], v[16:17], off nt
	v_or_b32_e32 v4, s10, v22
	v_lshlrev_b64 v[16:17], 12, v[4:5]
	v_lshl_add_u64 v[16:17], v[14:15], 0, v[16:17]
	global_load_dwordx4 v[72:75], v[16:17], off nt
	v_or_b32_e32 v4, s10, v23
	v_lshlrev_b64 v[16:17], 12, v[4:5]
	v_lshl_add_u64 v[16:17], v[14:15], 0, v[16:17]
	global_load_dwordx4 v[76:79], v[16:17], off nt
	v_or_b32_e32 v4, s10, v24
	v_lshlrev_b64 v[16:17], 12, v[4:5]
	v_lshl_add_u64 v[16:17], v[14:15], 0, v[16:17]
	global_load_dwordx4 v[80:83], v[16:17], off nt
	v_or_b32_e32 v4, s10, v25
	v_lshlrev_b64 v[16:17], 12, v[4:5]
	v_lshl_add_u64 v[16:17], v[14:15], 0, v[16:17]
	global_load_dwordx4 v[84:87], v[16:17], off nt
	v_or_b32_e32 v4, s10, v26
	v_lshlrev_b64 v[16:17], 12, v[4:5]
	v_lshl_add_u64 v[16:17], v[14:15], 0, v[16:17]
	global_load_dwordx4 v[88:91], v[16:17], off nt
	s_waitcnt vmcnt(7)
	v_pk_mul_f32 v[60:61], v[92:93], v[60:61] op_sel_hi:[0,1]
	v_pk_mul_f32 v[62:63], v[92:93], v[62:63] op_sel_hi:[0,1]
	ds_write2_b32 v28, v60, v61 offset1:1
	ds_write2_b32 v28, v62, v63 offset0:2 offset1:3
	s_waitcnt vmcnt(6)
	v_pk_mul_f32 v[64:65], v[94:95], v[64:65] op_sel_hi:[0,1]
	v_pk_mul_f32 v[66:67], v[94:95], v[66:67] op_sel_hi:[0,1]
	v_add_u32_e32 v13, 0x420, v28
	v_add_u32_e32 v17, 0x428, v28
	ds_write2_b32 v13, v64, v65 offset1:1
	ds_write2_b32 v17, v66, v67 offset1:1
	s_waitcnt vmcnt(5)
	v_pk_mul_f32 v[68:69], v[96:97], v[68:69] op_sel_hi:[0,1]
	v_pk_mul_f32 v[70:71], v[96:97], v[70:71] op_sel_hi:[0,1]
	v_add_u32_e32 v13, 0x840, v28
	v_add_u32_e32 v17, 0x848, v28
	ds_write2_b32 v13, v68, v69 offset1:1
	ds_write2_b32 v17, v70, v71 offset1:1
	s_waitcnt vmcnt(4)
	v_pk_mul_f32 v[72:73], v[98:99], v[72:73] op_sel_hi:[0,1]
	v_pk_mul_f32 v[74:75], v[98:99], v[74:75] op_sel_hi:[0,1]
	v_add_u32_e32 v13, 0xc60, v28
	v_add_u32_e32 v17, 0xc68, v28
	ds_write2_b32 v13, v72, v73 offset1:1
	ds_write2_b32 v17, v74, v75 offset1:1
	s_waitcnt vmcnt(3)
	v_pk_mul_f32 v[76:77], v[100:101], v[76:77] op_sel_hi:[0,1]
	v_pk_mul_f32 v[78:79], v[100:101], v[78:79] op_sel_hi:[0,1]
	v_add_u32_e32 v13, 0x1080, v28
	v_add_u32_e32 v17, 0x1088, v28
	ds_write2_b32 v13, v76, v77 offset1:1
	ds_write2_b32 v17, v78, v79 offset1:1
	s_waitcnt vmcnt(2)
	v_pk_mul_f32 v[80:81], v[102:103], v[80:81] op_sel_hi:[0,1]
	v_pk_mul_f32 v[82:83], v[102:103], v[82:83] op_sel_hi:[0,1]
	v_add_u32_e32 v13, 0x14a0, v28
	v_add_u32_e32 v17, 0x14a8, v28
	ds_write2_b32 v13, v80, v81 offset1:1
	ds_write2_b32 v17, v82, v83 offset1:1
	s_waitcnt vmcnt(1)
	v_pk_mul_f32 v[84:85], v[104:105], v[84:85] op_sel_hi:[0,1]
	v_pk_mul_f32 v[86:87], v[104:105], v[86:87] op_sel_hi:[0,1]
	v_add_u32_e32 v13, 0x18c0, v28
	v_add_u32_e32 v17, 0x18c8, v28
	ds_write2_b32 v13, v84, v85 offset1:1
	ds_write2_b32 v17, v86, v87 offset1:1
	s_waitcnt vmcnt(0)
	v_pk_mul_f32 v[88:89], v[106:107], v[88:89] op_sel_hi:[0,1]
	v_pk_mul_f32 v[90:91], v[106:107], v[90:91] op_sel_hi:[0,1]
	v_add_u32_e32 v13, 0x1ce0, v28
	v_add_u32_e32 v17, 0x1ce8, v28
	ds_write2_b32 v13, v88, v89 offset1:1
	ds_write2_b32 v17, v90, v91 offset1:1
	s_mov_b64 s[4:5], 0
	s_waitcnt lgkmcnt(0)
	ds_read2_b32 v[14:15], v27 offset1:33
	s_waitcnt lgkmcnt(0)
	v_cvt_pk_bf16_f32 v14, v14, v15
	ds_read2_b32 v[16:17], v27 offset0:66 offset1:99
	v_or_b32_e32 v4, s77, v2
	s_waitcnt lgkmcnt(0)
	v_cvt_pk_bf16_f32 v15, v16, v17
	ds_read2_b32 v[16:17], v27 offset0:132 offset1:165
	v_lshl_add_u64 v[30:31], s[10:11], 1, v[6:7]
	v_lshlrev_b32_e32 v4, 11, v4
	s_waitcnt lgkmcnt(0)
	v_cvt_pk_bf16_f32 v16, v16, v17
	ds_read2_b32 v[18:19], v27 offset0:198 offset1:231
	s_waitcnt lgkmcnt(0)
	v_cvt_pk_bf16_f32 v17, v18, v19
	v_lshl_add_u64 v[32:33], v[30:31], 0, v[4:5]
	ds_read2_b32 v[18:19], v27 offset0:8 offset1:41
	global_store_dwordx4 v[32:33], v[14:17], off
	v_or_b32_e32 v4, s77, v20
	v_lshlrev_b32_e32 v4, 11, v4
	s_waitcnt lgkmcnt(0)
	v_cvt_pk_bf16_f32 v14, v18, v19
	ds_read2_b32 v[16:17], v27 offset0:74 offset1:107
	s_waitcnt lgkmcnt(0)
	v_cvt_pk_bf16_f32 v15, v16, v17
	ds_read2_b32 v[16:17], v27 offset0:140 offset1:173
	s_waitcnt lgkmcnt(0)
	v_cvt_pk_bf16_f32 v16, v16, v17
	ds_read2_b32 v[18:19], v27 offset0:206 offset1:239
	s_waitcnt lgkmcnt(0)
	v_cvt_pk_bf16_f32 v17, v18, v19
	v_lshl_add_u64 v[32:33], v[30:31], 0, v[4:5]
	ds_read2_b32 v[18:19], v27 offset0:16 offset1:49
	global_store_dwordx4 v[32:33], v[14:17], off
	v_or_b32_e32 v4, s77, v21
	v_lshlrev_b32_e32 v4, 11, v4
	s_waitcnt lgkmcnt(0)
	v_cvt_pk_bf16_f32 v14, v18, v19
	ds_read2_b32 v[16:17], v27 offset0:82 offset1:115
	s_waitcnt lgkmcnt(0)
	v_cvt_pk_bf16_f32 v15, v16, v17
	ds_read2_b32 v[16:17], v27 offset0:148 offset1:181
	s_waitcnt lgkmcnt(0)
	v_cvt_pk_bf16_f32 v16, v16, v17
	ds_read2_b32 v[18:19], v27 offset0:214 offset1:247
	s_waitcnt lgkmcnt(0)
	v_cvt_pk_bf16_f32 v17, v18, v19
	v_lshl_add_u64 v[32:33], v[30:31], 0, v[4:5]
	ds_read2_b32 v[18:19], v27 offset0:24 offset1:57
	global_store_dwordx4 v[32:33], v[14:17], off
	v_or_b32_e32 v4, s77, v22
	v_lshlrev_b32_e32 v4, 11, v4
	s_waitcnt lgkmcnt(0)
	v_cvt_pk_bf16_f32 v14, v18, v19
	ds_read2_b32 v[16:17], v27 offset0:90 offset1:123
	s_waitcnt lgkmcnt(0)
	v_cvt_pk_bf16_f32 v15, v16, v17
	ds_read2_b32 v[16:17], v27 offset0:156 offset1:189
	s_waitcnt lgkmcnt(0)
	v_cvt_pk_bf16_f32 v16, v16, v17
	ds_read2_b32 v[18:19], v27 offset0:222 offset1:255
	s_waitcnt lgkmcnt(0)
	v_cvt_pk_bf16_f32 v17, v18, v19
	v_lshl_add_u64 v[18:19], v[30:31], 0, v[4:5]
	global_store_dwordx4 v[18:19], v[14:17], off
	s_waitcnt lgkmcnt(0)

.LBB0_131:
	s_andn2_b64 vcc, exec, s[4:5]
	s_cbranch_vccnz .LBB0_92
	v_mov_b32_e32 v4, s75
	ds_read2_b64 v[14:17], v4 offset1:1
	s_mul_hi_i32 s4, s64, 0x2aaaaaab
	s_lshr_b32 s5, s4, 31
	s_ashr_i32 s10, s4, 3
	s_add_i32 s10, s10, s5
	s_lshl_b32 s54, s10, 6
	s_ashr_i32 s55, s54, 31
	s_waitcnt lgkmcnt(0)
	v_readfirstlane_b32 s58, v14
	v_readfirstlane_b32 s59, v15
	v_readfirstlane_b32 s4, v16
	v_readfirstlane_b32 s5, v17
	s_mulk_i32 s10, 0xfa00
	s_add_i32 s56, s66, s10
	s_ashr_i32 s57, s56, 31
	s_lshl_b64 s[78:79], s[56:57], 2
	s_add_u32 s4, s4, s78
	s_addc_u32 s5, s5, s79
	v_mov_b32_e32 v13, v5
	v_lshl_add_u64 v[14:15], s[4:5], 0, v[12:13]
	s_cmp_eq_u64 s[58:59], 0
	s_cbranch_scc1 .Lwi_noscale
	v_lshl_add_u64 v[16:17], s[54:55], 0, v[2:3]
	v_lshl_add_u64 v[16:17], v[16:17], 2, s[58:59]
	global_load_dword v92, v[16:17], off
	global_load_dword v94, v[16:17], off offset:32
	global_load_dword v96, v[16:17], off offset:64
	global_load_dword v98, v[16:17], off offset:96
	global_load_dword v100, v[16:17], off offset:128
	global_load_dword v102, v[16:17], off offset:160
	global_load_dword v104, v[16:17], off offset:192
	global_load_dword v106, v[16:17], off offset:224
	s_branch .Lwi_w

.Lwi_w:
	v_or_b32_e32 v13, s54, v2
	v_mad_i64_i32 v[18:19], s[4:5], v13, s76, v[14:15]
	global_load_dwordx4 v[60:63], v[18:19], off nt
	v_or_b32_e32 v13, s54, v20
	v_mad_i64_i32 v[18:19], s[4:5], v13, s76, v[14:15]
	global_load_dwordx4 v[64:67], v[18:19], off nt
	v_or_b32_e32 v13, s54, v21
	v_mad_i64_i32 v[18:19], s[4:5], v13, s76, v[14:15]
	global_load_dwordx4 v[68:71], v[18:19], off nt
	v_or_b32_e32 v13, s54, v22
	v_mad_i64_i32 v[18:19], s[4:5], v13, s76, v[14:15]
	global_load_dwordx4 v[72:75], v[18:19], off nt
	v_or_b32_e32 v13, s54, v23
	v_mad_i64_i32 v[18:19], s[4:5], v13, s76, v[14:15]
	global_load_dwordx4 v[76:79], v[18:19], off nt
	v_or_b32_e32 v13, s54, v24
	v_mad_i64_i32 v[18:19], s[4:5], v13, s76, v[14:15]
	global_load_dwordx4 v[80:83], v[18:19], off nt
	v_or_b32_e32 v13, s54, v25
	v_mad_i64_i32 v[18:19], s[4:5], v13, s76, v[14:15]
	global_load_dwordx4 v[84:87], v[18:19], off nt
	v_or_b32_e32 v13, s54, v26
	v_mad_i64_i32 v[18:19], s[4:5], v13, s76, v[14:15]
	global_load_dwordx4 v[88:91], v[18:19], off nt
	s_waitcnt vmcnt(7)
	v_pk_mul_f32 v[60:61], v[92:93], v[60:61] op_sel_hi:[0,1]
	v_pk_mul_f32 v[62:63], v[92:93], v[62:63] op_sel_hi:[0,1]
	ds_write2_b32 v28, v60, v61 offset1:1
	ds_write2_b32 v28, v62, v63 offset0:2 offset1:3
	s_waitcnt vmcnt(6)
	v_pk_mul_f32 v[64:65], v[94:95], v[64:65] op_sel_hi:[0,1]
	v_pk_mul_f32 v[66:67], v[94:95], v[66:67] op_sel_hi:[0,1]
	v_add_u32_e32 v13, 0x420, v28
	v_add_u32_e32 v17, 0x428, v28
	ds_write2_b32 v13, v64, v65 offset1:1
	ds_write2_b32 v17, v66, v67 offset1:1
	s_waitcnt vmcnt(5)
	v_pk_mul_f32 v[68:69], v[96:97], v[68:69] op_sel_hi:[0,1]
	v_pk_mul_f32 v[70:71], v[96:97], v[70:71] op_sel_hi:[0,1]
	v_add_u32_e32 v13, 0x840, v28
	v_add_u32_e32 v17, 0x848, v28
	ds_write2_b32 v13, v68, v69 offset1:1
	ds_write2_b32 v17, v70, v71 offset1:1
	s_waitcnt vmcnt(4)
	v_pk_mul_f32 v[72:73], v[98:99], v[72:73] op_sel_hi:[0,1]
	v_pk_mul_f32 v[74:75], v[98:99], v[74:75] op_sel_hi:[0,1]
	v_add_u32_e32 v13, 0xc60, v28
	v_add_u32_e32 v17, 0xc68, v28
	ds_write2_b32 v13, v72, v73 offset1:1
	ds_write2_b32 v17, v74, v75 offset1:1
	s_waitcnt vmcnt(3)
	v_pk_mul_f32 v[76:77], v[100:101], v[76:77] op_sel_hi:[0,1]
	v_pk_mul_f32 v[78:79], v[100:101], v[78:79] op_sel_hi:[0,1]
	v_add_u32_e32 v13, 0x1080, v28
	v_add_u32_e32 v17, 0x1088, v28
	ds_write2_b32 v13, v76, v77 offset1:1
	ds_write2_b32 v17, v78, v79 offset1:1
	s_waitcnt vmcnt(2)
	v_pk_mul_f32 v[80:81], v[102:103], v[80:81] op_sel_hi:[0,1]
	v_pk_mul_f32 v[82:83], v[102:103], v[82:83] op_sel_hi:[0,1]
	v_add_u32_e32 v13, 0x14a0, v28
	v_add_u32_e32 v17, 0x14a8, v28
	ds_write2_b32 v13, v80, v81 offset1:1
	ds_write2_b32 v17, v82, v83 offset1:1
	s_waitcnt vmcnt(1)
	v_pk_mul_f32 v[84:85], v[104:105], v[84:85] op_sel_hi:[0,1]
	v_pk_mul_f32 v[86:87], v[104:105], v[86:87] op_sel_hi:[0,1]
	v_add_u32_e32 v13, 0x18c0, v28
	v_add_u32_e32 v17, 0x18c8, v28
	ds_write2_b32 v13, v84, v85 offset1:1
	ds_write2_b32 v17, v86, v87 offset1:1
	s_waitcnt vmcnt(0)
	v_pk_mul_f32 v[88:89], v[106:107], v[88:89] op_sel_hi:[0,1]
	v_pk_mul_f32 v[90:91], v[106:107], v[90:91] op_sel_hi:[0,1]
	v_add_u32_e32 v13, 0x1ce0, v28
	v_add_u32_e32 v17, 0x1ce8, v28
	ds_write2_b32 v13, v88, v89 offset1:1
	ds_write2_b32 v17, v90, v91 offset1:1
	s_branch .LBB0_91
